# DIFF: PV(sub1) V-ring fill and P packing issued under the last PV(sub0) MFMAs, no cvt/read lump between the two PV chains
# speedup vs baseline: 1.0074x; 1.0047x over previous
; #define MFMA(a, b, c) __builtin_amdgcn_mfma_f32_32x32x16_bf16((a), (b), (c), 0, 0, 0)
; DI u32 pk2(float a, float b) { f2_t v = {a, b}; bf2_t r = __builtin_convertvector(v, bf2_t); return __builtin_bit_cast(u32, r); }
; #define DIFF_MASK(sv, sub_) do { if (needmask) { _Pragma("unroll") for (int r = 0; r < 16; ++r) { const int kl_ = (sub_) * 32 + ((r < 8) ? (8 * g2 + r) : (16 + 8 * g2 + (r - 8))); \
;           if ((pki[kl_] >> 6) > (((int)qposf) >> 6)) sv[r] = -__builtin_inff(); } } } while (0)
; template <bool DIFF>
; DI void attn_phase(const AttnArgs& a, char* lds) {
;     ...
;           float ps = 0.f;
; #pragma unroll
;           for (int r = 0; r < 16; ++r) { s0[r] = __builtin_amdgcn_exp2f(s0[r]); ps += s0[r]; }
;           l_sum += ps;
;           asm volatile("" : "+v"(l_sum));
; #pragma unroll
;           for (int i = 0; i < NDS; ++i) { __builtin_amdgcn_sched_group_barrier(0x008, 1, 0); __builtin_amdgcn_sched_group_barrier(0x002, 9, 0); }
;         }
;         __builtin_amdgcn_sched_barrier(0);
;         {
;           bf16x8 vf[NM];
; #pragma unroll
;           for (int s2 = 0; s2 < 2; ++s2) {
; #pragma unroll
;             for (int m = 0; m < NM; ++m) vf[m] = *(const bf16x8*)(sb + voffb + m * 4096 + (((2 * s2) ^ vx) << 4));
;             u32x4 pw;
;             pw[0] = pk2(s0[8 * s2], s0[8 * s2 + 1]); pw[1] = pk2(s0[8 * s2 + 2], s0[8 * s2 + 3]);
;             pw[2] = pk2(s0[8 * s2 + 4], s0[8 * s2 + 5]); pw[3] = pk2(s0[8 * s2 + 6], s0[8 * s2 + 7]);
;             const bf16x8 pf = __builtin_bit_cast(bf16x8, pw);
; #pragma unroll
;             for (int m = 0; m < NM; ++m) o[m] = MFMA(vf[m], pf, o[m]);
;           }
;           DIFF_ALIBI(s1, 1);
;           DIFF_MASK(s1, 1);
.LBB0_605:
	v_exp_f32_e32 v11, v11
	v_exp_f32_e32 v9, v9
	v_exp_f32_e32 v10, v10
	v_exp_f32_e32 v8, v8
	v_bitop3_b32 v0, v0, v3, 7 bitop3:0x78
	v_add_f32_e32 v3, 0, v11
	v_exp_f32_e32 v165, v7
	v_add_f32_e32 v3, v9, v3
	v_exp_f32_e32 v166, v6
	v_add_f32_e32 v3, v10, v3
	v_exp_f32_e32 v167, v5
	v_add_f32_e32 v3, v8, v3
	v_exp_f32_e32 v168, v4
	v_add_f32_e32 v3, v165, v3
	v_exp_f32_e32 v164, v164
	v_lshlrev_b32_e32 v2, 7, v2
	v_add_f32_e32 v3, v166, v3
	v_exp_f32_e32 v169, v162
	v_and_b32_e32 v2, 0xf80, v2
	v_add_f32_e32 v3, v167, v3
	v_exp_f32_e32 v170, v160
	v_add_f32_e32 v3, v168, v3
	v_exp_f32_e32 v171, v161
	v_add_f32_e32 v3, v164, v3
	v_exp_f32_e32 v15, v15
	v_add_f32_e32 v3, v169, v3
	v_exp_f32_e32 v14, v14
	v_add_f32_e32 v3, v170, v3
	v_exp_f32_e32 v172, v13
	v_add_f32_e32 v3, v171, v3
	v_exp_f32_e32 v173, v12
	v_add_f32_e32 v3, v15, v3
	v_add_f32_e32 v3, v14, v3
	v_add_f32_e32 v3, v172, v3
	v_add_f32_e32 v3, v173, v3
	v_add_f32_e32 v162, v226, v3
	v_add_u32_e32 v160, s84, v2
	v_lshlrev_b32_e32 v161, 4, v0
	v_add_u32_e32 v0, v160, v161
	v_cvt_pk_bf16_f32 v6, v11, v9
	v_cvt_pk_bf16_f32 v7, v10, v8
	v_cvt_pk_bf16_f32 v8, v165, v166
	v_cvt_pk_bf16_f32 v9, v167, v168
	v_cvt_pk_bf16_f32 v10, v164, v169
	v_cvt_pk_bf16_f32 v11, v170, v171
	v_cvt_pk_bf16_f32 v12, v15, v14
	v_cvt_pk_bf16_f32 v13, v172, v173
	v_add_u32_e32 v14, 0x10180, v227
	v_xad_u32 v15, v161, 32, v160
	ds_read_b128 v[164:167], v14
	ds_read_b128 v[168:171], v14 offset:16
	ds_read_b128 v[172:175], v14 offset:64
	ds_read_b128 v[248:251], v14 offset:80
	ds_read_b128 v[2:5], v0 offset:32768
	ds_read_b128 v[228:231], v0 offset:36864
	ds_read_b128 v[232:235], v0 offset:40960
	ds_read_b128 v[236:239], v0 offset:45056
	ds_read_b128 v[240:243], v0 offset:49152
	ds_read_b128 v[244:247], v0 offset:53248
	s_and_b64 vcc, exec, s[8:9]
	s_waitcnt lgkmcnt(5)
	v_mfma_f32_32x32x16_bf16 v[128:143], v[2:5], v[6:9], v[128:143]
	ds_read_b128 v[2:5], v0 offset:57344
	v_sub_f32_e32 v164, v221, v164
	v_sub_f32_e32 v165, v221, v165
	v_fma_f32 v164, -v223, |v164|, v144
	v_fma_f32 v165, -v223, |v165|, v145
	s_waitcnt lgkmcnt(5)
	v_mfma_f32_32x32x16_bf16 v[112:127], v[228:231], v[6:9], v[112:127]
	ds_read_b128 v[228:231], v0 offset:61440
	v_sub_f32_e32 v166, v221, v166
	v_sub_f32_e32 v167, v221, v167
	v_fma_f32 v166, -v223, |v166|, v146
	v_fma_f32 v167, -v223, |v167|, v147
	s_waitcnt lgkmcnt(5)
	v_mfma_f32_32x32x16_bf16 v[96:111], v[232:235], v[6:9], v[96:111]
	ds_read_b128 v[232:235], v15 offset:32768
	v_sub_f32_e32 v168, v221, v168
	v_sub_f32_e32 v169, v221, v169
	v_fma_f32 v168, -v223, |v168|, v148
	v_fma_f32 v169, -v223, |v169|, v149
	s_waitcnt lgkmcnt(5)
	v_mfma_f32_32x32x16_bf16 v[80:95], v[236:239], v[6:9], v[80:95]
	ds_read_b128 v[236:239], v15 offset:36864
	v_sub_f32_e32 v170, v221, v170
	v_sub_f32_e32 v171, v221, v171
	v_fma_f32 v170, -v223, |v170|, v150
	v_fma_f32 v171, -v223, |v171|, v151
	s_waitcnt lgkmcnt(5)
	v_mfma_f32_32x32x16_bf16 v[64:79], v[240:243], v[6:9], v[64:79]
	ds_read_b128 v[240:243], v15 offset:40960
	v_sub_f32_e32 v172, v221, v172
	v_sub_f32_e32 v173, v221, v173
	v_fma_f32 v172, -v223, |v172|, v152
	v_fma_f32 v173, -v223, |v173|, v153
	s_waitcnt lgkmcnt(5)
	v_mfma_f32_32x32x16_bf16 v[48:63], v[244:247], v[6:9], v[48:63]
	ds_read_b128 v[244:247], v15 offset:45056
	v_sub_f32_e32 v174, v221, v174
	v_sub_f32_e32 v175, v221, v175
	v_fma_f32 v174, -v223, |v174|, v154
	v_fma_f32 v175, -v223, |v175|, v155
	s_waitcnt lgkmcnt(5)
	v_mfma_f32_32x32x16_bf16 v[32:47], v[2:5], v[6:9], v[32:47]
	ds_read_b128 v[2:5], v15 offset:49152
	v_sub_f32_e32 v248, v221, v248
	v_sub_f32_e32 v249, v221, v249
	v_fma_f32 v248, -v223, |v248|, v156
	v_fma_f32 v249, -v223, |v249|, v157
	s_waitcnt lgkmcnt(5)
	v_mfma_f32_32x32x16_bf16 v[16:31], v[228:231], v[6:9], v[16:31]
	ds_read_b128 v[228:231], v15 offset:53248
	v_sub_f32_e32 v250, v221, v250
	v_sub_f32_e32 v251, v221, v251
	v_fma_f32 v250, -v223, |v250|, v158
	v_fma_f32 v251, -v223, |v251|, v159
	v_xad_u32 v156, v161, 64, v160
	s_cbranch_vccnz .Ldiff_nomask1
	ds_read_b128 v[146:149], v163 offset:128
	s_waitcnt lgkmcnt(0)
	v_ashrrev_i32_e32 v144, 6, v146
	v_cmp_le_i32_e32 vcc, v144, v224
	v_ashrrev_i32_e32 v144, 6, v147
	s_nop 0
	v_cndmask_b32_e32 v164, v216, v164, vcc
	v_cmp_le_i32_e32 vcc, v144, v224
	v_ashrrev_i32_e32 v144, 6, v148
	s_nop 0
	v_cndmask_b32_e32 v165, v216, v165, vcc
	v_cmp_le_i32_e32 vcc, v144, v224
	v_ashrrev_i32_e32 v144, 6, v149
	s_nop 0
	v_cndmask_b32_e32 v166, v216, v166, vcc
	v_cmp_le_i32_e32 vcc, v144, v224
	v_add_u32_e32 v144, 0x10090, v227
	ds_read_b128 v[146:149], v144
	v_cndmask_b32_e32 v167, v216, v167, vcc
	s_waitcnt lgkmcnt(0)
	v_ashrrev_i32_e32 v144, 6, v146
	v_cmp_le_i32_e32 vcc, v144, v224
	v_ashrrev_i32_e32 v144, 6, v147
	s_nop 0
	v_cndmask_b32_e32 v168, v216, v168, vcc
	v_cmp_le_i32_e32 vcc, v144, v224
	v_ashrrev_i32_e32 v144, 6, v148
	s_nop 0
	v_cndmask_b32_e32 v169, v216, v169, vcc
	v_cmp_le_i32_e32 vcc, v144, v224
	v_ashrrev_i32_e32 v144, 6, v149
	s_nop 0
	v_cndmask_b32_e32 v170, v216, v170, vcc
	v_cmp_le_i32_e32 vcc, v144, v224
	v_add_u32_e32 v144, 0x100c0, v227
	ds_read_b128 v[146:149], v144
	v_cndmask_b32_e32 v171, v216, v171, vcc
	s_waitcnt lgkmcnt(0)
	v_ashrrev_i32_e32 v144, 6, v146
	v_cmp_le_i32_e32 vcc, v144, v224
	v_ashrrev_i32_e32 v144, 6, v147
	s_nop 0
	v_cndmask_b32_e32 v172, v216, v172, vcc
	v_cmp_le_i32_e32 vcc, v144, v224
	v_ashrrev_i32_e32 v144, 6, v148
	s_nop 0
	v_cndmask_b32_e32 v173, v216, v173, vcc
	v_cmp_le_i32_e32 vcc, v144, v224
	v_ashrrev_i32_e32 v144, 6, v149
	s_nop 0
	v_cndmask_b32_e32 v174, v216, v174, vcc
	v_cmp_le_i32_e32 vcc, v144, v224
	v_add_u32_e32 v144, 0x100d0, v227
	ds_read_b128 v[146:149], v144
	v_cndmask_b32_e32 v175, v216, v175, vcc
	s_waitcnt lgkmcnt(0)
	v_ashrrev_i32_e32 v144, 6, v146
	v_cmp_le_i32_e32 vcc, v144, v224
	v_ashrrev_i32_e32 v144, 6, v147
	s_nop 0
	v_cndmask_b32_e32 v248, v216, v248, vcc
	v_cmp_le_i32_e32 vcc, v144, v224
	v_ashrrev_i32_e32 v144, 6, v148
	s_nop 0
	v_cndmask_b32_e32 v249, v216, v249, vcc
	v_cmp_le_i32_e32 vcc, v144, v224
	v_ashrrev_i32_e32 v144, 6, v149
	s_nop 0
	v_cndmask_b32_e32 v250, v216, v250, vcc
	v_cmp_le_i32_e32 vcc, v144, v224
	s_nop 1
	v_cndmask_b32_e32 v251, v216, v251, vcc
; #define MFMA(a, b, c) __builtin_amdgcn_mfma_f32_32x32x16_bf16((a), (b), (c), 0, 0, 0)
; DI u32 pk2(float a, float b) { f2_t v = {a, b}; bf2_t r = __builtin_convertvector(v, bf2_t); return __builtin_bit_cast(u32, r); }
; template <bool DIFF>
; DI void attn_phase(const AttnArgs& a, char* lds) {
;     ...
;           float ps = 0.f;
; #pragma unroll
;           for (int r = 0; r < 16; ++r) { s1[r] = __builtin_amdgcn_exp2f(s1[r]); ps += s1[r]; }
;           l_sum += ps;
;           asm volatile("" : "+v"(l_sum));
; #pragma unroll
;           for (int i = 0; i < 2 * NM; ++i) { __builtin_amdgcn_sched_group_barrier(0x008, 1, 0); __builtin_amdgcn_sched_group_barrier(0x002, 4, 0); }
;         }
;         __builtin_amdgcn_sched_barrier(0);
;         {
; #pragma unroll
;           for (int s2 = 0; s2 < 2; ++s2) {
;             bf16x8 vf[NM];
; #pragma unroll
;             for (int m = 0; m < NM; ++m) vf[m] = *(const bf16x8*)(sb + voffb + m * 4096 + (((4 + 2 * s2) ^ vx) << 4));
;             u32x4 pw;
;             pw[0] = pk2(s1[8 * s2], s1[8 * s2 + 1]); pw[1] = pk2(s1[8 * s2 + 2], s1[8 * s2 + 3]);
;             pw[2] = pk2(s1[8 * s2 + 4], s1[8 * s2 + 5]); pw[3] = pk2(s1[8 * s2 + 6], s1[8 * s2 + 7]);
;             const bf16x8 pf = __builtin_bit_cast(bf16x8, pw);
; #pragma unroll
;             for (int m = 0; m < NM; ++m) o[m] = MFMA(vf[m], pf, o[m]);
;           }
.Ldiff_nomask1:
	s_waitcnt lgkmcnt(5)
	v_mfma_f32_32x32x16_bf16 v[128:143], v[232:235], v[10:13], v[128:143]
	ds_read_b128 v[232:235], v15 offset:57344
	v_exp_f32_e32 v0, v164
	v_exp_f32_e32 v9, v165
	v_add_f32_e32 v253, 0, v0
	v_add_f32_e32 v253, v9, v253
	s_waitcnt lgkmcnt(5)
	v_mfma_f32_32x32x16_bf16 v[112:127], v[236:239], v[10:13], v[112:127]
	ds_read_b128 v[236:239], v15 offset:61440
	v_exp_f32_e32 v144, v166
	v_exp_f32_e32 v146, v167
	v_add_f32_e32 v253, v144, v253
	v_add_f32_e32 v253, v146, v253
	s_waitcnt lgkmcnt(5)
	v_mfma_f32_32x32x16_bf16 v[96:111], v[240:243], v[10:13], v[96:111]
	ds_read_b128 v[240:243], v156 offset:32768
	v_exp_f32_e32 v147, v168
	v_exp_f32_e32 v148, v169
	v_add_f32_e32 v253, v147, v253
	v_add_f32_e32 v253, v148, v253
	s_waitcnt lgkmcnt(5)
	v_mfma_f32_32x32x16_bf16 v[80:95], v[244:247], v[10:13], v[80:95]
	ds_read_b128 v[244:247], v156 offset:36864
	v_exp_f32_e32 v149, v170
	v_exp_f32_e32 v150, v171
	v_add_f32_e32 v253, v149, v253
	v_add_f32_e32 v253, v150, v253
	s_waitcnt lgkmcnt(5)
	v_mfma_f32_32x32x16_bf16 v[64:79], v[2:5], v[10:13], v[64:79]
	ds_read_b128 v[2:5], v156 offset:40960
	v_exp_f32_e32 v151, v172
	v_exp_f32_e32 v145, v173
	v_add_f32_e32 v253, v151, v253
	v_add_f32_e32 v253, v145, v253
	v_cvt_pk_bf16_f32 v6, v0, v9
	v_cvt_pk_bf16_f32 v7, v144, v146
	s_waitcnt lgkmcnt(5)
	v_mfma_f32_32x32x16_bf16 v[48:63], v[228:231], v[10:13], v[48:63]
	ds_read_b128 v[228:231], v156 offset:45056
	v_exp_f32_e32 v152, v174
	v_exp_f32_e32 v153, v175
	v_add_f32_e32 v253, v152, v253
	v_add_f32_e32 v253, v153, v253
	v_cvt_pk_bf16_f32 v8, v147, v148
	v_cvt_pk_bf16_f32 v9, v149, v150
	v_xad_u32 v0, v161, s74, v160
	s_waitcnt lgkmcnt(5)
	v_mfma_f32_32x32x16_bf16 v[32:47], v[232:235], v[10:13], v[32:47]
	ds_read_b128 v[232:235], v156 offset:49152
	v_exp_f32_e32 v154, v248
	v_exp_f32_e32 v155, v249
	v_add_f32_e32 v253, v154, v253
	v_add_f32_e32 v253, v155, v253
	s_waitcnt lgkmcnt(5)
	v_mfma_f32_32x32x16_bf16 v[16:31], v[236:239], v[10:13], v[16:31]
	ds_read_b128 v[236:239], v156 offset:53248
	v_exp_f32_e32 v14, v250
	v_exp_f32_e32 v15, v251
	v_add_f32_e32 v253, v14, v253
	v_add_f32_e32 v253, v15, v253
	v_add_f32_e32 v226, v162, v253
	ds_read_b128 v[248:251], v156 offset:57344
	s_waitcnt lgkmcnt(6)
	v_mfma_f32_32x32x16_bf16 v[128:143], v[240:243], v[6:9], v[128:143]
	ds_read_b128 v[240:243], v156 offset:61440
	v_cvt_pk_bf16_f32 v10, v151, v145
	v_cvt_pk_bf16_f32 v11, v152, v153
	s_waitcnt lgkmcnt(6)
	v_mfma_f32_32x32x16_bf16 v[112:127], v[244:247], v[6:9], v[112:127]
	ds_read_b128 v[244:247], v0 offset:32768
	v_cvt_pk_bf16_f32 v12, v154, v155
	v_cvt_pk_bf16_f32 v13, v14, v15
	s_waitcnt lgkmcnt(6)
	v_mfma_f32_32x32x16_bf16 v[96:111], v[2:5], v[6:9], v[96:111]
	ds_read_b128 v[2:5], v0 offset:36864
	s_waitcnt lgkmcnt(6)
	v_mfma_f32_32x32x16_bf16 v[80:95], v[228:231], v[6:9], v[80:95]
	ds_read_b128 v[228:231], v0 offset:40960
	s_waitcnt lgkmcnt(6)
	v_mfma_f32_32x32x16_bf16 v[64:79], v[232:235], v[6:9], v[64:79]
	ds_read_b128 v[232:235], v0 offset:45056
	s_waitcnt lgkmcnt(6)
	v_mfma_f32_32x32x16_bf16 v[48:63], v[236:239], v[6:9], v[48:63]
	ds_read_b128 v[236:239], v0 offset:49152
	s_waitcnt lgkmcnt(6)
	v_mfma_f32_32x32x16_bf16 v[32:47], v[248:251], v[6:9], v[32:47]
	ds_read_b128 v[248:251], v0 offset:53248
	s_waitcnt lgkmcnt(6)
	v_mfma_f32_32x32x16_bf16 v[16:31], v[240:243], v[6:9], v[16:31]
	ds_read_b128 v[240:243], v0 offset:57344
	s_waitcnt lgkmcnt(6)
	v_mfma_f32_32x32x16_bf16 v[128:143], v[244:247], v[10:13], v[128:143]
	ds_read_b128 v[244:247], v0 offset:61440
	s_waitcnt lgkmcnt(6)
	v_mfma_f32_32x32x16_bf16 v[112:127], v[2:5], v[10:13], v[112:127]
	s_waitcnt lgkmcnt(5)
	v_mfma_f32_32x32x16_bf16 v[96:111], v[228:231], v[10:13], v[96:111]
	s_waitcnt lgkmcnt(4)
	v_mfma_f32_32x32x16_bf16 v[80:95], v[232:235], v[10:13], v[80:95]
	s_waitcnt lgkmcnt(3)
	v_mfma_f32_32x32x16_bf16 v[64:79], v[236:239], v[10:13], v[64:79]
	s_waitcnt lgkmcnt(2)
	v_mfma_f32_32x32x16_bf16 v[48:63], v[248:251], v[10:13], v[48:63]
	s_waitcnt lgkmcnt(1)
	v_mfma_f32_32x32x16_bf16 v[32:47], v[240:243], v[10:13], v[32:47]
	s_waitcnt lgkmcnt(0)
	v_mfma_f32_32x32x16_bf16 v[16:31], v[244:247], v[10:13], v[16:31]
